# grid-barrier poll loops keep two staggered sc1 polls of TOP in flight (destinations v252/v242, dead registers; no drain at exit)
# speedup vs baseline: 1.0005x; 1.0005x over previous
; __device__ __forceinline__ unsigned xb_ld(unsigned* p)              { return __hip_atomic_load(p, __ATOMIC_RELAXED, __HIP_MEMORY_SCOPE_AGENT); }
; __device__ __forceinline__ unsigned xb_add(unsigned* p, unsigned v) { return __hip_atomic_fetch_add(p, v, __ATOMIC_RELAXED, __HIP_MEMORY_SCOPE_AGENT); }
; #define XB_SPIN(cond, bar) do { unsigned _sp = 0; while (cond) { __builtin_amdgcn_s_sleep(1); \
;     if ((++_sp & 255u) == 0u) { if (xb_ld(&(bar)[XB_TMO])) break; if (_sp > XB_SPIN_CAP) { atomicAdd(&(bar)[XB_TMO], 1u); break; } } } } while (0)
; __device__ __forceinline__ void grid_bar(int wv, unsigned* bar, volatile LAS unsigned* st) {
;     ...
;             const unsigned og = xb_add(&bar[XB_TOP], 1u);
;             const unsigned tg = og / nx;
;             if (og + 1u == (tg + 1u) * nx) xb_add(&bar[XB_TOPGEN], 1u);
;             else XB_SPIN(xb_ld(&bar[XB_TOPGEN]) == tg, bar);
.Lgb_loop_0:
	global_load_dword v252, v4, s[10:11] sc1
	s_sleep 16
	global_load_dword v242, v4, s[10:11] sc1
.Lgb_roll_0:
	s_waitcnt vmcnt(1)
	v_readfirstlane_b32 s101, v252
	s_cmp_ge_u32 s101, s2
	s_cbranch_scc1 .Lgb_done_0
	global_load_dword v252, v4, s[10:11] sc1
	s_waitcnt vmcnt(1)
	v_readfirstlane_b32 s101, v242
	s_cmp_ge_u32 s101, s2
	s_cbranch_scc1 .Lgb_done_0
	global_load_dword v242, v4, s[10:11] sc1
	s_add_i32 s1, s1, 1
	s_bitcmp1_b32 s1, 17
	s_cbranch_scc0 .Lgb_roll_0

; __device__ __forceinline__ unsigned xb_ld(unsigned* p)              { return __hip_atomic_load(p, __ATOMIC_RELAXED, __HIP_MEMORY_SCOPE_AGENT); }
; __device__ __forceinline__ unsigned xb_add(unsigned* p, unsigned v) { return __hip_atomic_fetch_add(p, v, __ATOMIC_RELAXED, __HIP_MEMORY_SCOPE_AGENT); }
; #define XB_SPIN(cond, bar) do { unsigned _sp = 0; while (cond) { __builtin_amdgcn_s_sleep(1); \
;     if ((++_sp & 255u) == 0u) { if (xb_ld(&(bar)[XB_TMO])) break; if (_sp > XB_SPIN_CAP) { atomicAdd(&(bar)[XB_TMO], 1u); break; } } } } while (0)
; __device__ __forceinline__ void grid_bar(int wv, unsigned* bar, volatile LAS unsigned* st) {
;     ...
;             const unsigned og = xb_add(&bar[XB_TOP], 1u);
;             const unsigned tg = og / nx;
;             if (og + 1u == (tg + 1u) * nx) xb_add(&bar[XB_TOPGEN], 1u);
;             else XB_SPIN(xb_ld(&bar[XB_TOPGEN]) == tg, bar);
.Lgb_loop_1:
	global_load_dword v252, v5, s[4:5] sc1
	s_sleep 16
	global_load_dword v242, v5, s[4:5] sc1
.Lgb_roll_1:
	s_waitcnt vmcnt(1)
	v_readfirstlane_b32 s101, v252
	s_cmp_ge_u32 s101, s1
	s_cbranch_scc1 .Lgb_done_1
	global_load_dword v252, v5, s[4:5] sc1
	s_waitcnt vmcnt(1)
	v_readfirstlane_b32 s101, v242
	s_cmp_ge_u32 s101, s1
	s_cbranch_scc1 .Lgb_done_1
	global_load_dword v242, v5, s[4:5] sc1
	s_add_i32 s0, s0, 1
	s_bitcmp1_b32 s0, 17
	s_cbranch_scc0 .Lgb_roll_1
